# gated-merge mini-unit gate loads issued together; out-GEMM split-K reduction loads its base row together with the slabs
# speedup vs baseline: 1.0001x; 1.0001x over previous
.LBB0_585:
	s_and_b64 vcc, exec, s[26:27]
	s_cbranch_vccz .LBB0_591
	v_lshl_add_u64 v[66:67], v[162:163], 0, v[174:175]
	v_lshl_add_u64 v[190:191], v[162:163], 0, v[174:175]
	global_load_dwordx2 v[192:193], v[190:191], off
	global_load_dwordx2 v[194:195], v[190:191], off offset:128
	v_lshl_add_u64 v[190:191], v[164:165], 0, v[174:175]
	global_load_dwordx2 v[196:197], v[190:191], off
	global_load_dwordx2 v[198:199], v[190:191], off offset:128
	v_lshl_add_u64 v[190:191], v[166:167], 0, v[174:175]
	global_load_dwordx2 v[200:201], v[190:191], off
	global_load_dwordx2 v[202:203], v[190:191], off offset:128
	v_lshl_add_u64 v[190:191], v[168:169], 0, v[174:175]
	global_load_dwordx2 v[204:205], v[190:191], off
	global_load_dwordx2 v[206:207], v[190:191], off offset:128
	s_waitcnt vmcnt(0)
	v_mov_b64_e32 v[68:69], v[192:193]
	s_add_i32 s8, s8, s56
	s_lshl_b64 s[26:27], s[8:9], 20
	s_add_u32 vcc_lo, s4, s26
	s_addc_u32 vcc_hi, s5, s27
	v_lshl_add_u64 v[70:71], vcc, 0, v[154:155]
	v_lshlrev_b64 v[64:65], 2, v[174:175]
	v_lshl_add_u64 v[70:71], v[70:71], 0, v[64:65]
	v_cvt_f32_ubyte3_e32 v73, v68
	v_cvt_f32_ubyte2_e32 v72, v68
	v_cvt_f32_ubyte1_e32 v75, v68
	v_cvt_f32_ubyte0_e32 v74, v68
	v_pk_mul_f32 v[74:75], v[74:75], s[74:75] op_sel_hi:[1,0]
	v_pk_mul_f32 v[72:73], v[72:73], s[74:75] op_sel_hi:[1,0]
	v_pk_mul_f32 v[60:61], v[60:61], v[74:75]
	v_pk_mul_f32 v[62:63], v[62:63], v[72:73]
	global_store_dwordx4 v[70:71], v[60:63], off
	s_nop 1
	v_cvt_f32_ubyte3_e32 v61, v69
	v_cvt_f32_ubyte2_e32 v60, v69
	v_cvt_f32_ubyte1_e32 v63, v69
	v_cvt_f32_ubyte0_e32 v62, v69
	v_pk_mul_f32 v[62:63], v[62:63], s[74:75] op_sel_hi:[1,0]
	v_pk_mul_f32 v[60:61], v[60:61], s[74:75] op_sel_hi:[1,0]
	v_pk_mul_f32 v[56:57], v[56:57], v[62:63]
	v_pk_mul_f32 v[58:59], v[58:59], v[60:61]
	global_store_dwordx4 v[70:71], v[56:59], off offset:16
	s_nop 1
	v_mov_b64_e32 v[56:57], v[194:195]
	v_cvt_f32_ubyte1_e32 v61, v56
	v_cvt_f32_ubyte3_e32 v59, v56
	v_cvt_f32_ubyte2_e32 v58, v56
	v_cvt_f32_ubyte0_e32 v60, v56
	v_pk_mul_f32 v[60:61], v[60:61], s[74:75] op_sel_hi:[1,0]
	v_pk_mul_f32 v[58:59], v[58:59], s[74:75] op_sel_hi:[1,0]
	v_pk_mul_f32 v[52:53], v[52:53], v[60:61]
	v_pk_mul_f32 v[54:55], v[54:55], v[58:59]
	global_store_dwordx4 v[70:71], v[52:55], off offset:512
	s_nop 1
	v_cvt_f32_ubyte3_e32 v53, v57
	v_cvt_f32_ubyte2_e32 v52, v57
	v_cvt_f32_ubyte1_e32 v55, v57
	v_cvt_f32_ubyte0_e32 v54, v57
	v_pk_mul_f32 v[54:55], v[54:55], s[74:75] op_sel_hi:[1,0]
	v_pk_mul_f32 v[52:53], v[52:53], s[74:75] op_sel_hi:[1,0]
	v_pk_mul_f32 v[48:49], v[48:49], v[54:55]
	v_pk_mul_f32 v[50:51], v[50:51], v[52:53]
	global_store_dwordx4 v[70:71], v[48:51], off offset:528
	v_lshl_add_u64 v[52:53], vcc, 0, v[156:157]
	v_lshl_add_u64 v[52:53], v[52:53], 0, v[64:65]
	v_lshl_add_u64 v[48:49], v[164:165], 0, v[174:175]
	v_mov_b64_e32 v[50:51], v[196:197]
	v_cvt_f32_ubyte3_e32 v55, v50
	v_cvt_f32_ubyte2_e32 v54, v50
	v_cvt_f32_ubyte1_e32 v57, v50
	v_cvt_f32_ubyte0_e32 v56, v50
	v_pk_mul_f32 v[56:57], v[56:57], s[74:75] op_sel_hi:[1,0]
	v_pk_mul_f32 v[54:55], v[54:55], s[74:75] op_sel_hi:[1,0]
	v_pk_mul_f32 v[44:45], v[44:45], v[56:57]
	v_pk_mul_f32 v[46:47], v[46:47], v[54:55]
	global_store_dwordx4 v[52:53], v[44:47], off
	s_nop 1
	v_cvt_f32_ubyte3_e32 v45, v51
	v_cvt_f32_ubyte2_e32 v44, v51
	v_cvt_f32_ubyte1_e32 v47, v51
	v_cvt_f32_ubyte0_e32 v46, v51
	v_pk_mul_f32 v[46:47], v[46:47], s[74:75] op_sel_hi:[1,0]
	v_pk_mul_f32 v[44:45], v[44:45], s[74:75] op_sel_hi:[1,0]
	v_pk_mul_f32 v[40:41], v[40:41], v[46:47]
	v_pk_mul_f32 v[42:43], v[42:43], v[44:45]
	global_store_dwordx4 v[52:53], v[40:43], off offset:16
	s_nop 1
	v_mov_b64_e32 v[40:41], v[198:199]
	v_cvt_f32_ubyte1_e32 v45, v40
	v_cvt_f32_ubyte3_e32 v43, v40
	v_cvt_f32_ubyte2_e32 v42, v40
	v_cvt_f32_ubyte0_e32 v44, v40
	v_pk_mul_f32 v[44:45], v[44:45], s[74:75] op_sel_hi:[1,0]
	v_pk_mul_f32 v[42:43], v[42:43], s[74:75] op_sel_hi:[1,0]
	v_pk_mul_f32 v[36:37], v[36:37], v[44:45]
	v_pk_mul_f32 v[38:39], v[38:39], v[42:43]
	global_store_dwordx4 v[52:53], v[36:39], off offset:512
	s_nop 1
	v_cvt_f32_ubyte3_e32 v37, v41
	v_cvt_f32_ubyte2_e32 v36, v41
	v_cvt_f32_ubyte1_e32 v39, v41
	v_cvt_f32_ubyte0_e32 v38, v41
	v_pk_mul_f32 v[38:39], v[38:39], s[74:75] op_sel_hi:[1,0]
	v_pk_mul_f32 v[36:37], v[36:37], s[74:75] op_sel_hi:[1,0]
	v_pk_mul_f32 v[32:33], v[32:33], v[38:39]
	v_pk_mul_f32 v[34:35], v[34:35], v[36:37]
	global_store_dwordx4 v[52:53], v[32:35], off offset:528
	v_lshl_add_u64 v[36:37], vcc, 0, v[158:159]
	v_lshl_add_u64 v[36:37], v[36:37], 0, v[64:65]
	v_lshl_add_u64 v[32:33], v[166:167], 0, v[174:175]
	v_mov_b64_e32 v[34:35], v[200:201]
	v_cvt_f32_ubyte3_e32 v39, v34
	v_cvt_f32_ubyte2_e32 v38, v34
	v_cvt_f32_ubyte1_e32 v41, v34
	v_cvt_f32_ubyte0_e32 v40, v34
	v_pk_mul_f32 v[40:41], v[40:41], s[74:75] op_sel_hi:[1,0]
	v_pk_mul_f32 v[38:39], v[38:39], s[74:75] op_sel_hi:[1,0]
	v_pk_mul_f32 v[28:29], v[28:29], v[40:41]
	v_pk_mul_f32 v[30:31], v[30:31], v[38:39]
	global_store_dwordx4 v[36:37], v[28:31], off
	s_nop 1
	v_cvt_f32_ubyte3_e32 v29, v35
	v_cvt_f32_ubyte2_e32 v28, v35
	v_cvt_f32_ubyte1_e32 v31, v35
	v_cvt_f32_ubyte0_e32 v30, v35
	v_pk_mul_f32 v[30:31], v[30:31], s[74:75] op_sel_hi:[1,0]
	v_pk_mul_f32 v[28:29], v[28:29], s[74:75] op_sel_hi:[1,0]
	v_pk_mul_f32 v[24:25], v[24:25], v[30:31]
	v_pk_mul_f32 v[26:27], v[26:27], v[28:29]
	global_store_dwordx4 v[36:37], v[24:27], off offset:16
	s_nop 1
	v_mov_b64_e32 v[24:25], v[202:203]
	v_cvt_f32_ubyte1_e32 v29, v24
	v_cvt_f32_ubyte3_e32 v27, v24
	v_cvt_f32_ubyte2_e32 v26, v24
	v_cvt_f32_ubyte0_e32 v28, v24
	v_pk_mul_f32 v[28:29], v[28:29], s[74:75] op_sel_hi:[1,0]
	v_pk_mul_f32 v[26:27], v[26:27], s[74:75] op_sel_hi:[1,0]
	v_pk_mul_f32 v[20:21], v[20:21], v[28:29]
	v_pk_mul_f32 v[22:23], v[22:23], v[26:27]
	global_store_dwordx4 v[36:37], v[20:23], off offset:512
	s_nop 1
	v_cvt_f32_ubyte3_e32 v21, v25
	v_cvt_f32_ubyte2_e32 v20, v25
	v_cvt_f32_ubyte1_e32 v23, v25
	v_cvt_f32_ubyte0_e32 v22, v25
	v_pk_mul_f32 v[22:23], v[22:23], s[74:75] op_sel_hi:[1,0]
	v_pk_mul_f32 v[20:21], v[20:21], s[74:75] op_sel_hi:[1,0]
	v_pk_mul_f32 v[16:17], v[16:17], v[22:23]
	v_pk_mul_f32 v[18:19], v[18:19], v[20:21]
	global_store_dwordx4 v[36:37], v[16:19], off offset:528
	v_lshl_add_u64 v[20:21], vcc, 0, v[160:161]
	v_lshl_add_u64 v[20:21], v[20:21], 0, v[64:65]
	v_lshl_add_u64 v[16:17], v[168:169], 0, v[174:175]
	v_mov_b64_e32 v[18:19], v[204:205]
	v_cvt_f32_ubyte3_e32 v23, v18
	v_cvt_f32_ubyte2_e32 v22, v18
	v_cvt_f32_ubyte1_e32 v25, v18
	v_cvt_f32_ubyte0_e32 v24, v18
	v_pk_mul_f32 v[24:25], v[24:25], s[74:75] op_sel_hi:[1,0]
	v_pk_mul_f32 v[22:23], v[22:23], s[74:75] op_sel_hi:[1,0]
	v_pk_mul_f32 v[12:13], v[12:13], v[24:25]
	v_pk_mul_f32 v[14:15], v[14:15], v[22:23]
	global_store_dwordx4 v[20:21], v[12:15], off
	s_nop 1
	v_cvt_f32_ubyte3_e32 v13, v19
	v_cvt_f32_ubyte2_e32 v12, v19
	v_cvt_f32_ubyte1_e32 v15, v19
	v_cvt_f32_ubyte0_e32 v14, v19
	v_pk_mul_f32 v[14:15], v[14:15], s[74:75] op_sel_hi:[1,0]
	v_pk_mul_f32 v[12:13], v[12:13], s[74:75] op_sel_hi:[1,0]
	v_pk_mul_f32 v[8:9], v[8:9], v[14:15]
	v_pk_mul_f32 v[10:11], v[10:11], v[12:13]
	global_store_dwordx4 v[20:21], v[8:11], off offset:16
	s_nop 1
	v_mov_b64_e32 v[8:9], v[206:207]
	v_cvt_f32_ubyte1_e32 v13, v8
	v_cvt_f32_ubyte3_e32 v11, v8
	v_cvt_f32_ubyte2_e32 v10, v8
	v_cvt_f32_ubyte0_e32 v12, v8
	v_pk_mul_f32 v[12:13], v[12:13], s[74:75] op_sel_hi:[1,0]
	v_pk_mul_f32 v[10:11], v[10:11], s[74:75] op_sel_hi:[1,0]
	v_pk_mul_f32 v[4:5], v[4:5], v[12:13]
	v_pk_mul_f32 v[6:7], v[6:7], v[10:11]
	global_store_dwordx4 v[20:21], v[4:7], off offset:512
	s_nop 1
	v_cvt_f32_ubyte3_e32 v5, v9
	v_cvt_f32_ubyte2_e32 v4, v9
	v_cvt_f32_ubyte1_e32 v7, v9
	v_cvt_f32_ubyte0_e32 v6, v9
	v_pk_mul_f32 v[6:7], v[6:7], s[74:75] op_sel_hi:[1,0]
	v_pk_mul_f32 v[4:5], v[4:5], s[74:75] op_sel_hi:[1,0]
	v_pk_mul_f32 v[0:1], v[0:1], v[6:7]
	v_pk_mul_f32 v[2:3], v[2:3], v[4:5]
	global_store_dwordx4 v[20:21], v[0:3], off offset:528
	s_waitcnt vmcnt(0)
	s_barrier
	s_and_saveexec_b64 s[26:27], s[18:19]
	s_cbranch_execz .LBB0_588
	s_lshl_b32 s34, s10, 6
	s_ashr_i32 s35, s34, 31
	s_lshl_b64 s[34:35], s[34:35], 2
	s_add_u32 s34, s75, s34
	s_addc_u32 s35, s21, s35
	buffer_wbl2 sc1
	s_waitcnt vmcnt(0)
	s_waitcnt vmcnt(0)
	v_mov_b64_e32 v[0:1], s[34:35]
	flat_atomic_add v0, v[0:1], v182 sc0
	s_waitcnt vmcnt(0) lgkmcnt(0)
	ds_write_b32 v145, v0
	v_mov_b64_e32 v[2:3], s[34:35]

.LBB0_821:
	v_add_u32_e32 v9, s2, v8
	s_waitcnt lgkmcnt(0)
	v_ashrrev_i32_e32 v10, 6, v9
	v_add_u32_e32 v6, 0x2000, v10
	v_ashrrev_i32_e32 v7, 31, v6
	v_lshlrev_b64 v[12:13], 12, v[6:7]
	v_lshl_add_u64 v[42:43], v[4:5], 0, v[12:13]
	global_load_dwordx2 v[60:61], v[42:43], off
	v_ashrrev_i32_e32 v11, 31, v10
	v_lshlrev_b64 v[10:11], 13, v[10:11]
	v_lshl_add_u64 v[38:39], v[0:1], 0, v[10:11]
	v_add_co_u32_e64 v14, s[0:1], s63, v38
	s_nop 1
	v_addc_co_u32_e64 v15, s[0:1], 0, v39, s[0:1]
	v_add_co_u32_e64 v18, s[0:1], s64, v38
	s_nop 0
	s_nop 0
	v_addc_co_u32_e64 v19, s[0:1], 0, v39, s[0:1]
	v_add_co_u32_e64 v22, s[0:1], s65, v38
	s_nop 0
	s_nop 0
	v_addc_co_u32_e64 v23, s[0:1], 0, v39, s[0:1]
	v_add_co_u32_e64 v26, s[0:1], s66, v38
	s_nop 0
	global_load_dwordx4 v[10:13], v[38:39], off
	v_addc_co_u32_e64 v27, s[0:1], 0, v39, s[0:1]
	global_load_dwordx4 v[14:17], v[14:15], off
	v_add_co_u32_e64 v30, s[0:1], s67, v38
	global_load_dwordx4 v[18:21], v[18:19], off
	s_nop 0
	v_addc_co_u32_e64 v31, s[0:1], 0, v39, s[0:1]
	global_load_dwordx4 v[22:25], v[22:23], off
	v_add_co_u32_e64 v34, s[0:1], s74, v38
	global_load_dwordx4 v[26:29], v[26:27], off
	s_nop 0
	v_addc_co_u32_e64 v35, s[0:1], 0, v39, s[0:1]
	global_load_dwordx4 v[30:33], v[30:31], off
	v_add_co_u32_e64 v38, s[0:1], s75, v38
	global_load_dwordx4 v[34:37], v[34:35], off
	s_nop 0
	v_addc_co_u32_e64 v39, s[0:1], 0, v39, s[0:1]
	global_load_dwordx4 v[38:41], v[38:39], off
	s_waitcnt vmcnt(7)
	v_lshlrev_b32_e32 v44, 16, v60
	v_and_b32_e32 v45, 0xffff0000, v60
	v_lshlrev_b32_e32 v46, 16, v61
	v_and_b32_e32 v47, 0xffff0000, v61
	v_pk_add_f32 v[10:11], v[10:11], v[44:45]
	v_pk_add_f32 v[12:13], v[12:13], v[46:47]
	s_waitcnt vmcnt(6)
	v_pk_add_f32 v[10:11], v[14:15], v[10:11]
	v_pk_add_f32 v[12:13], v[16:17], v[12:13]
	s_waitcnt vmcnt(5)
	v_pk_add_f32 v[10:11], v[18:19], v[10:11]
	v_pk_add_f32 v[12:13], v[20:21], v[12:13]
	s_waitcnt vmcnt(4)
	v_pk_add_f32 v[10:11], v[22:23], v[10:11]
	v_pk_add_f32 v[12:13], v[24:25], v[12:13]
	s_waitcnt vmcnt(3)
	v_pk_add_f32 v[10:11], v[26:27], v[10:11]
	v_pk_add_f32 v[12:13], v[28:29], v[12:13]
	s_waitcnt vmcnt(2)
	v_pk_add_f32 v[10:11], v[30:31], v[10:11]
	v_pk_add_f32 v[12:13], v[32:33], v[12:13]
	s_waitcnt vmcnt(1)
	v_pk_add_f32 v[10:11], v[34:35], v[10:11]
	v_pk_add_f32 v[12:13], v[36:37], v[12:13]
	s_waitcnt vmcnt(0)
	v_pk_add_f32 v[10:11], v[38:39], v[10:11]
	v_pk_add_f32 v[12:13], v[40:41], v[12:13]
	s_nop 1
	v_cvt_pk_bf16_f32 v14, v10, v11
	v_mul_f32_e32 v11, v11, v11
	v_fmac_f32_e32 v11, v10, v10
	v_mul_f32_e32 v10, v13, v13
	v_fmac_f32_e32 v10, v12, v12
	s_nop 1
	v_cvt_pk_bf16_f32 v15, v12, v13
	v_add_f32_e32 v11, v11, v10
	v_and_b32_e32 v10, 64, v164
	global_store_dwordx2 v[42:43], v[14:15], off
	v_add_u32_e32 v15, 64, v10
	v_xor_b32_e32 v10, 1, v164
	v_cmp_lt_i32_e64 s[0:1], v10, v15
	s_nop 1
	v_cndmask_b32_e64 v10, v164, v10, s[0:1]
	v_lshlrev_b32_e32 v10, 2, v10
	ds_bpermute_b32 v12, v10, v11
	s_waitcnt lgkmcnt(0)
	v_add_f32_e32 v12, v11, v12
	v_xor_b32_e32 v11, 2, v164
	v_cmp_lt_i32_e64 s[0:1], v11, v15
	s_nop 1
	v_cndmask_b32_e64 v11, v164, v11, s[0:1]
	v_lshlrev_b32_e32 v11, 2, v11
	ds_bpermute_b32 v13, v11, v12
	s_waitcnt lgkmcnt(0)
	v_add_f32_e32 v13, v12, v13
	v_xor_b32_e32 v12, 4, v164
	v_cmp_lt_i32_e64 s[0:1], v12, v15
	s_nop 1
	v_cndmask_b32_e64 v12, v164, v12, s[0:1]
	v_lshlrev_b32_e32 v12, 2, v12
	ds_bpermute_b32 v14, v12, v13
	s_waitcnt lgkmcnt(0)
	v_add_f32_e32 v14, v13, v14
	v_xor_b32_e32 v13, 8, v164
	v_cmp_lt_i32_e64 s[0:1], v13, v15
	s_nop 1
	v_cndmask_b32_e64 v13, v164, v13, s[0:1]
	v_lshlrev_b32_e32 v13, 2, v13
	ds_bpermute_b32 v16, v13, v14
	s_waitcnt lgkmcnt(0)
	v_add_f32_e32 v16, v14, v16
	v_xor_b32_e32 v14, 16, v164
	v_cmp_lt_i32_e64 s[0:1], v14, v15
	s_nop 1
	v_cndmask_b32_e64 v14, v164, v14, s[0:1]
	v_lshlrev_b32_e32 v14, 2, v14
	ds_bpermute_b32 v17, v14, v16
	s_waitcnt lgkmcnt(0)
	v_add_f32_e32 v16, v16, v17
	v_xor_b32_e32 v17, 32, v164
	v_cmp_lt_i32_e64 s[0:1], v17, v15
	s_nop 1
	v_cndmask_b32_e64 v15, v164, v17, s[0:1]
	v_lshlrev_b32_e32 v15, 2, v15
	ds_bpermute_b32 v17, v15, v16
	s_and_saveexec_b64 s[0:1], vcc
	s_cbranch_execz .LBB0_823
	s_waitcnt lgkmcnt(0)
	v_add_f32_e32 v16, v16, v17
	v_lshlrev_b64 v[6:7], 7, v[6:7]
	v_cndmask_b32_e64 v16, 0, v16, s[10:11]
	v_lshl_add_u64 v[6:7], v[2:3], 0, v[6:7]
	flat_store_dword v[6:7], v16 sc1

.LBB0_1520:
	s_and_b64 vcc, exec, s[8:9]
	s_cbranch_vccz .LBB0_1526
	v_lshl_add_u64 v[66:67], v[162:163], 0, v[174:175]
	v_lshl_add_u64 v[190:191], v[162:163], 0, v[174:175]
	global_load_dwordx2 v[192:193], v[190:191], off
	global_load_dwordx2 v[194:195], v[190:191], off offset:128
	v_lshl_add_u64 v[190:191], v[164:165], 0, v[174:175]
	global_load_dwordx2 v[196:197], v[190:191], off
	global_load_dwordx2 v[198:199], v[190:191], off offset:128
	v_lshl_add_u64 v[190:191], v[166:167], 0, v[174:175]
	global_load_dwordx2 v[200:201], v[190:191], off
	global_load_dwordx2 v[202:203], v[190:191], off offset:128
	v_lshl_add_u64 v[190:191], v[168:169], 0, v[174:175]
	global_load_dwordx2 v[204:205], v[190:191], off
	global_load_dwordx2 v[206:207], v[190:191], off offset:128
	s_waitcnt vmcnt(0)
	v_mov_b64_e32 v[68:69], v[192:193]
	s_add_i32 s4, s4, s81
	s_lshl_b64 s[8:9], s[4:5], 20
	s_add_u32 s64, s10, s8
	s_addc_u32 s65, s11, s9
	v_lshl_add_u64 v[70:71], s[64:65], 0, v[154:155]
	v_lshlrev_b64 v[64:65], 2, v[174:175]
	v_lshl_add_u64 v[70:71], v[70:71], 0, v[64:65]
	v_cvt_f32_ubyte3_e32 v73, v68
	v_cvt_f32_ubyte2_e32 v72, v68
	v_cvt_f32_ubyte1_e32 v75, v68
	v_cvt_f32_ubyte0_e32 v74, v68
	v_pk_mul_f32 v[74:75], v[74:75], s[36:37] op_sel_hi:[1,0]
	v_pk_mul_f32 v[72:73], v[72:73], s[36:37] op_sel_hi:[1,0]
	v_pk_mul_f32 v[60:61], v[60:61], v[74:75]
	v_pk_mul_f32 v[62:63], v[62:63], v[72:73]
	global_store_dwordx4 v[70:71], v[60:63], off
	s_nop 1
	v_cvt_f32_ubyte3_e32 v61, v69
	v_cvt_f32_ubyte2_e32 v60, v69
	v_cvt_f32_ubyte1_e32 v63, v69
	v_cvt_f32_ubyte0_e32 v62, v69
	v_pk_mul_f32 v[62:63], v[62:63], s[36:37] op_sel_hi:[1,0]
	v_pk_mul_f32 v[60:61], v[60:61], s[36:37] op_sel_hi:[1,0]
	v_pk_mul_f32 v[56:57], v[56:57], v[62:63]
	v_pk_mul_f32 v[58:59], v[58:59], v[60:61]
	global_store_dwordx4 v[70:71], v[56:59], off offset:16
	s_nop 1
	v_mov_b64_e32 v[56:57], v[194:195]
	v_cvt_f32_ubyte1_e32 v61, v56
	v_cvt_f32_ubyte3_e32 v59, v56
	v_cvt_f32_ubyte2_e32 v58, v56
	v_cvt_f32_ubyte0_e32 v60, v56
	v_pk_mul_f32 v[60:61], v[60:61], s[36:37] op_sel_hi:[1,0]
	v_pk_mul_f32 v[58:59], v[58:59], s[36:37] op_sel_hi:[1,0]
	v_pk_mul_f32 v[52:53], v[52:53], v[60:61]
	v_pk_mul_f32 v[54:55], v[54:55], v[58:59]
	global_store_dwordx4 v[70:71], v[52:55], off offset:512
	s_nop 1
	v_cvt_f32_ubyte3_e32 v53, v57
	v_cvt_f32_ubyte2_e32 v52, v57
	v_cvt_f32_ubyte1_e32 v55, v57
	v_cvt_f32_ubyte0_e32 v54, v57
	v_pk_mul_f32 v[54:55], v[54:55], s[36:37] op_sel_hi:[1,0]
	v_pk_mul_f32 v[52:53], v[52:53], s[36:37] op_sel_hi:[1,0]
	v_pk_mul_f32 v[48:49], v[48:49], v[54:55]
	v_pk_mul_f32 v[50:51], v[50:51], v[52:53]
	global_store_dwordx4 v[70:71], v[48:51], off offset:528
	v_lshl_add_u64 v[52:53], s[64:65], 0, v[156:157]
	v_lshl_add_u64 v[52:53], v[52:53], 0, v[64:65]
	v_lshl_add_u64 v[48:49], v[164:165], 0, v[174:175]
	v_mov_b64_e32 v[50:51], v[196:197]
	v_cvt_f32_ubyte3_e32 v55, v50
	v_cvt_f32_ubyte2_e32 v54, v50
	v_cvt_f32_ubyte1_e32 v57, v50
	v_cvt_f32_ubyte0_e32 v56, v50
	v_pk_mul_f32 v[56:57], v[56:57], s[36:37] op_sel_hi:[1,0]
	v_pk_mul_f32 v[54:55], v[54:55], s[36:37] op_sel_hi:[1,0]
	v_pk_mul_f32 v[44:45], v[44:45], v[56:57]
	v_pk_mul_f32 v[46:47], v[46:47], v[54:55]
	global_store_dwordx4 v[52:53], v[44:47], off
	s_nop 1
	v_cvt_f32_ubyte3_e32 v45, v51
	v_cvt_f32_ubyte2_e32 v44, v51
	v_cvt_f32_ubyte1_e32 v47, v51
	v_cvt_f32_ubyte0_e32 v46, v51
	v_pk_mul_f32 v[46:47], v[46:47], s[36:37] op_sel_hi:[1,0]
	v_pk_mul_f32 v[44:45], v[44:45], s[36:37] op_sel_hi:[1,0]
	v_pk_mul_f32 v[40:41], v[40:41], v[46:47]
	v_pk_mul_f32 v[42:43], v[42:43], v[44:45]
	global_store_dwordx4 v[52:53], v[40:43], off offset:16
	s_nop 1
	v_mov_b64_e32 v[40:41], v[198:199]
	v_cvt_f32_ubyte1_e32 v45, v40
	v_cvt_f32_ubyte3_e32 v43, v40
	v_cvt_f32_ubyte2_e32 v42, v40
	v_cvt_f32_ubyte0_e32 v44, v40
	v_pk_mul_f32 v[44:45], v[44:45], s[36:37] op_sel_hi:[1,0]
	v_pk_mul_f32 v[42:43], v[42:43], s[36:37] op_sel_hi:[1,0]
	v_pk_mul_f32 v[36:37], v[36:37], v[44:45]
	v_pk_mul_f32 v[38:39], v[38:39], v[42:43]
	global_store_dwordx4 v[52:53], v[36:39], off offset:512
	s_nop 1
	v_cvt_f32_ubyte3_e32 v37, v41
	v_cvt_f32_ubyte2_e32 v36, v41
	v_cvt_f32_ubyte1_e32 v39, v41
	v_cvt_f32_ubyte0_e32 v38, v41
	v_pk_mul_f32 v[38:39], v[38:39], s[36:37] op_sel_hi:[1,0]
	v_pk_mul_f32 v[36:37], v[36:37], s[36:37] op_sel_hi:[1,0]
	v_pk_mul_f32 v[32:33], v[32:33], v[38:39]
	v_pk_mul_f32 v[34:35], v[34:35], v[36:37]
	global_store_dwordx4 v[52:53], v[32:35], off offset:528
	v_lshl_add_u64 v[36:37], s[64:65], 0, v[158:159]
	v_lshl_add_u64 v[36:37], v[36:37], 0, v[64:65]
	v_lshl_add_u64 v[32:33], v[166:167], 0, v[174:175]
	v_mov_b64_e32 v[34:35], v[200:201]
	v_cvt_f32_ubyte3_e32 v39, v34
	v_cvt_f32_ubyte2_e32 v38, v34
	v_cvt_f32_ubyte1_e32 v41, v34
	v_cvt_f32_ubyte0_e32 v40, v34
	v_pk_mul_f32 v[40:41], v[40:41], s[36:37] op_sel_hi:[1,0]
	v_pk_mul_f32 v[38:39], v[38:39], s[36:37] op_sel_hi:[1,0]
	v_pk_mul_f32 v[28:29], v[28:29], v[40:41]
	v_pk_mul_f32 v[30:31], v[30:31], v[38:39]
	global_store_dwordx4 v[36:37], v[28:31], off
	s_nop 1
	v_cvt_f32_ubyte3_e32 v29, v35
	v_cvt_f32_ubyte2_e32 v28, v35
	v_cvt_f32_ubyte1_e32 v31, v35
	v_cvt_f32_ubyte0_e32 v30, v35
	v_pk_mul_f32 v[30:31], v[30:31], s[36:37] op_sel_hi:[1,0]
	v_pk_mul_f32 v[28:29], v[28:29], s[36:37] op_sel_hi:[1,0]
	v_pk_mul_f32 v[24:25], v[24:25], v[30:31]
	v_pk_mul_f32 v[26:27], v[26:27], v[28:29]
	global_store_dwordx4 v[36:37], v[24:27], off offset:16
	s_nop 1
	v_mov_b64_e32 v[24:25], v[202:203]
	v_cvt_f32_ubyte1_e32 v29, v24
	v_cvt_f32_ubyte3_e32 v27, v24
	v_cvt_f32_ubyte2_e32 v26, v24
	v_cvt_f32_ubyte0_e32 v28, v24
	v_pk_mul_f32 v[28:29], v[28:29], s[36:37] op_sel_hi:[1,0]
	v_pk_mul_f32 v[26:27], v[26:27], s[36:37] op_sel_hi:[1,0]
	v_pk_mul_f32 v[20:21], v[20:21], v[28:29]
	v_pk_mul_f32 v[22:23], v[22:23], v[26:27]
	global_store_dwordx4 v[36:37], v[20:23], off offset:512
	s_nop 1
	v_cvt_f32_ubyte3_e32 v21, v25
	v_cvt_f32_ubyte2_e32 v20, v25
	v_cvt_f32_ubyte1_e32 v23, v25
	v_cvt_f32_ubyte0_e32 v22, v25
	v_pk_mul_f32 v[22:23], v[22:23], s[36:37] op_sel_hi:[1,0]
	v_pk_mul_f32 v[20:21], v[20:21], s[36:37] op_sel_hi:[1,0]
	v_pk_mul_f32 v[16:17], v[16:17], v[22:23]
	v_pk_mul_f32 v[18:19], v[18:19], v[20:21]
	global_store_dwordx4 v[36:37], v[16:19], off offset:528
	v_lshl_add_u64 v[20:21], s[64:65], 0, v[160:161]
	v_lshl_add_u64 v[20:21], v[20:21], 0, v[64:65]
	v_lshl_add_u64 v[16:17], v[168:169], 0, v[174:175]
	v_mov_b64_e32 v[18:19], v[204:205]
	v_cvt_f32_ubyte3_e32 v23, v18
	v_cvt_f32_ubyte2_e32 v22, v18
	v_cvt_f32_ubyte1_e32 v25, v18
	v_cvt_f32_ubyte0_e32 v24, v18
	v_pk_mul_f32 v[24:25], v[24:25], s[36:37] op_sel_hi:[1,0]
	v_pk_mul_f32 v[22:23], v[22:23], s[36:37] op_sel_hi:[1,0]
	v_pk_mul_f32 v[12:13], v[12:13], v[24:25]
	v_pk_mul_f32 v[14:15], v[14:15], v[22:23]
	global_store_dwordx4 v[20:21], v[12:15], off
	s_nop 1
	v_cvt_f32_ubyte3_e32 v13, v19
	v_cvt_f32_ubyte2_e32 v12, v19
	v_cvt_f32_ubyte1_e32 v15, v19
	v_cvt_f32_ubyte0_e32 v14, v19
	v_pk_mul_f32 v[14:15], v[14:15], s[36:37] op_sel_hi:[1,0]
	v_pk_mul_f32 v[12:13], v[12:13], s[36:37] op_sel_hi:[1,0]
	v_pk_mul_f32 v[8:9], v[8:9], v[14:15]
	v_pk_mul_f32 v[10:11], v[10:11], v[12:13]
	global_store_dwordx4 v[20:21], v[8:11], off offset:16
	s_nop 1
	v_mov_b64_e32 v[8:9], v[206:207]
	v_cvt_f32_ubyte1_e32 v13, v8
	v_cvt_f32_ubyte3_e32 v11, v8
	v_cvt_f32_ubyte2_e32 v10, v8
	v_cvt_f32_ubyte0_e32 v12, v8
	v_pk_mul_f32 v[12:13], v[12:13], s[36:37] op_sel_hi:[1,0]
	v_pk_mul_f32 v[10:11], v[10:11], s[36:37] op_sel_hi:[1,0]
	v_pk_mul_f32 v[4:5], v[4:5], v[12:13]
	v_pk_mul_f32 v[6:7], v[6:7], v[10:11]
	global_store_dwordx4 v[20:21], v[4:7], off offset:512
	s_nop 1
	v_cvt_f32_ubyte3_e32 v5, v9
	v_cvt_f32_ubyte2_e32 v4, v9
	v_cvt_f32_ubyte1_e32 v7, v9
	v_cvt_f32_ubyte0_e32 v6, v9
	v_pk_mul_f32 v[6:7], v[6:7], s[36:37] op_sel_hi:[1,0]
	v_pk_mul_f32 v[4:5], v[4:5], s[36:37] op_sel_hi:[1,0]
	v_pk_mul_f32 v[0:1], v[0:1], v[6:7]
	v_pk_mul_f32 v[2:3], v[2:3], v[4:5]
	global_store_dwordx4 v[20:21], v[0:3], off offset:528
	s_waitcnt vmcnt(0)
	s_barrier
	s_and_saveexec_b64 s[8:9], s[18:19]
	s_cbranch_execz .LBB0_1523
	s_lshl_b32 s64, s84, 6
	s_ashr_i32 s65, s64, 31
	s_lshl_b64 s[64:65], s[64:65], 2
	s_add_u32 s64, s37, s64
	s_addc_u32 s65, s53, s65
	buffer_wbl2 sc1
	s_waitcnt vmcnt(0)
	s_waitcnt vmcnt(0)
	v_mov_b64_e32 v[0:1], s[64:65]
	flat_atomic_add v0, v[0:1], v182 sc0
	s_waitcnt vmcnt(0) lgkmcnt(0)
	ds_write_b32 v145, v0
	v_mov_b64_e32 v[2:3], s[64:65]

.LBB0_1754:
	v_add_u32_e32 v9, s6, v8
	s_waitcnt lgkmcnt(0)
	v_ashrrev_i32_e32 v10, 6, v9
	v_add_u32_e32 v6, 0x2000, v10
	v_ashrrev_i32_e32 v7, 31, v6
	v_lshlrev_b64 v[12:13], 12, v[6:7]
	v_lshl_add_u64 v[42:43], v[4:5], 0, v[12:13]
	global_load_dwordx2 v[60:61], v[42:43], off
	v_ashrrev_i32_e32 v11, 31, v10
	v_lshlrev_b64 v[10:11], 13, v[10:11]
	v_lshl_add_u64 v[38:39], v[0:1], 0, v[10:11]
	v_add_co_u32_e64 v14, s[0:1], s67, v38
	s_nop 1
	v_addc_co_u32_e64 v15, s[0:1], 0, v39, s[0:1]
	v_add_co_u32_e64 v18, s[0:1], s72, v38
	s_nop 0
	s_nop 0
	v_addc_co_u32_e64 v19, s[0:1], 0, v39, s[0:1]
	v_add_co_u32_e64 v22, s[0:1], s73, v38
	s_nop 0
	s_nop 0
	v_addc_co_u32_e64 v23, s[0:1], 0, v39, s[0:1]
	v_add_co_u32_e64 v26, s[0:1], s74, v38
	s_nop 0
	global_load_dwordx4 v[10:13], v[38:39], off
	v_addc_co_u32_e64 v27, s[0:1], 0, v39, s[0:1]
	global_load_dwordx4 v[14:17], v[14:15], off
	v_add_co_u32_e64 v30, s[0:1], s75, v38
	global_load_dwordx4 v[18:21], v[18:19], off
	s_nop 0
	v_addc_co_u32_e64 v31, s[0:1], 0, v39, s[0:1]
	global_load_dwordx4 v[22:25], v[22:23], off
	v_add_co_u32_e64 v34, s[0:1], s76, v38
	global_load_dwordx4 v[26:29], v[26:27], off
	s_nop 0
	v_addc_co_u32_e64 v35, s[0:1], 0, v39, s[0:1]
	global_load_dwordx4 v[30:33], v[30:31], off
	v_add_co_u32_e64 v38, s[0:1], s77, v38
	global_load_dwordx4 v[34:37], v[34:35], off
	s_nop 0
	v_addc_co_u32_e64 v39, s[0:1], 0, v39, s[0:1]
	global_load_dwordx4 v[38:41], v[38:39], off
	s_waitcnt vmcnt(7)
	v_lshlrev_b32_e32 v44, 16, v60
	v_and_b32_e32 v45, 0xffff0000, v60
	v_lshlrev_b32_e32 v46, 16, v61
	v_and_b32_e32 v47, 0xffff0000, v61
	v_pk_add_f32 v[10:11], v[10:11], v[44:45]
	v_pk_add_f32 v[12:13], v[12:13], v[46:47]
	s_waitcnt vmcnt(6)
	v_pk_add_f32 v[10:11], v[14:15], v[10:11]
	v_pk_add_f32 v[12:13], v[16:17], v[12:13]
	s_waitcnt vmcnt(5)
	v_pk_add_f32 v[10:11], v[18:19], v[10:11]
	v_pk_add_f32 v[12:13], v[20:21], v[12:13]
	s_waitcnt vmcnt(4)
	v_pk_add_f32 v[10:11], v[22:23], v[10:11]
	v_pk_add_f32 v[12:13], v[24:25], v[12:13]
	s_waitcnt vmcnt(3)
	v_pk_add_f32 v[10:11], v[26:27], v[10:11]
	v_pk_add_f32 v[12:13], v[28:29], v[12:13]
	s_waitcnt vmcnt(2)
	v_pk_add_f32 v[10:11], v[30:31], v[10:11]
	v_pk_add_f32 v[12:13], v[32:33], v[12:13]
	s_waitcnt vmcnt(1)
	v_pk_add_f32 v[10:11], v[34:35], v[10:11]
	v_pk_add_f32 v[12:13], v[36:37], v[12:13]
	s_waitcnt vmcnt(0)
	v_pk_add_f32 v[10:11], v[38:39], v[10:11]
	v_pk_add_f32 v[12:13], v[40:41], v[12:13]
	s_nop 1
	v_cvt_pk_bf16_f32 v14, v10, v11
	v_mul_f32_e32 v11, v11, v11
	v_fmac_f32_e32 v11, v10, v10
	v_mul_f32_e32 v10, v13, v13
	v_fmac_f32_e32 v10, v12, v12
	s_nop 1
	v_cvt_pk_bf16_f32 v15, v12, v13
	v_add_f32_e32 v11, v11, v10
	v_and_b32_e32 v10, 64, v164
	global_store_dwordx2 v[42:43], v[14:15], off
	v_add_u32_e32 v15, 64, v10
	v_xor_b32_e32 v10, 1, v164
	v_cmp_lt_i32_e64 s[0:1], v10, v15
	s_nop 1
	v_cndmask_b32_e64 v10, v164, v10, s[0:1]
	v_lshlrev_b32_e32 v10, 2, v10
	ds_bpermute_b32 v12, v10, v11
	s_waitcnt lgkmcnt(0)
	v_add_f32_e32 v12, v11, v12
	v_xor_b32_e32 v11, 2, v164
	v_cmp_lt_i32_e64 s[0:1], v11, v15
	s_nop 1
	v_cndmask_b32_e64 v11, v164, v11, s[0:1]
	v_lshlrev_b32_e32 v11, 2, v11
	ds_bpermute_b32 v13, v11, v12
	s_waitcnt lgkmcnt(0)
	v_add_f32_e32 v13, v12, v13
	v_xor_b32_e32 v12, 4, v164
	v_cmp_lt_i32_e64 s[0:1], v12, v15
	s_nop 1
	v_cndmask_b32_e64 v12, v164, v12, s[0:1]
	v_lshlrev_b32_e32 v12, 2, v12
	ds_bpermute_b32 v14, v12, v13
	s_waitcnt lgkmcnt(0)
	v_add_f32_e32 v14, v13, v14
	v_xor_b32_e32 v13, 8, v164
	v_cmp_lt_i32_e64 s[0:1], v13, v15
	s_nop 1
	v_cndmask_b32_e64 v13, v164, v13, s[0:1]
	v_lshlrev_b32_e32 v13, 2, v13
	ds_bpermute_b32 v16, v13, v14
	s_waitcnt lgkmcnt(0)
	v_add_f32_e32 v16, v14, v16
	v_xor_b32_e32 v14, 16, v164
	v_cmp_lt_i32_e64 s[0:1], v14, v15
	s_nop 1
	v_cndmask_b32_e64 v14, v164, v14, s[0:1]
	v_lshlrev_b32_e32 v14, 2, v14
	ds_bpermute_b32 v17, v14, v16
	s_waitcnt lgkmcnt(0)
	v_add_f32_e32 v16, v16, v17
	v_xor_b32_e32 v17, 32, v164
	v_cmp_lt_i32_e64 s[0:1], v17, v15
	s_nop 1
	v_cndmask_b32_e64 v15, v164, v17, s[0:1]
	v_lshlrev_b32_e32 v15, 2, v15
	ds_bpermute_b32 v17, v15, v16
	s_and_saveexec_b64 s[0:1], vcc
	s_cbranch_execz .LBB0_1756
	s_waitcnt lgkmcnt(0)
	v_add_f32_e32 v16, v16, v17
	v_lshlrev_b64 v[6:7], 7, v[6:7]
	v_cndmask_b32_e64 v16, 0, v16, s[4:5]
	v_lshl_add_u64 v[6:7], v[2:3], 0, v[6:7]
	flat_store_dword v[6:7], v16 sc1
